# attention loop top waits only for the prefetched loads (vmcnt(8)), not for the previous iteration's output stores
# speedup vs baseline: 1.0030x; 1.0030x over previous
; #define LAS __attribute__((address_space(3)))
; __device__ __forceinline__ void attn_phase(LAS unsigned char* lds, int vcu, int G, const bf16* Qp, const bf16* Kp, const bf16* Vt, const float* sinks, bf16* AO, int ldo, float* st) {
;     ...
;     const int lane = tid & 63, wave = __builtin_amdgcn_readfirstlane(tid >> 6), r32 = lane & 31, hi = lane >> 5, hq = wave & 3, qsub = wave >> 2;
;     const float NEG = -INFINITY;
;     float ssq_acc = 0.f;
;     for (int it = 0; it < 4; ++it) { const int id = ((vcu >> 5) << 7) | (it << 5) | (vcu & 31);
;         const int b = id >> 7, kvh = (id >> 5) & 3, q0 = 64 * (id & 31), h = kvh * 4 + hq;
;         const size_t tok0 = (size_t)b * SEQ;
;         const int jt0 = (q0 >= 128) ? 0 : (128 - q0) / 32;
;         v4u kv[3], vv[3];
; #pragma unroll
;         for (int i = 0; i < 3; ++i) { const int c = tid + 512 * i, row = c >> 3, ch = c & 7, key = q0 - 128 + row;
;             if (key >= 0) kv[i] = *(const v4u*)(Kp + (tok0 + key) * D_KV + kvh * HD + ch * 8); }
; #pragma unroll
;         for (int i = 0; i < 3; ++i) { const int c = tid + 512 * i, d = c / 24, ch = c - d * 24, key0 = q0 - 128 + 8 * ch;
;             if (key0 >= 0) vv[i] = *(const v4u*)(Vt + (size_t)(kvh * HD + d) * M + tok0 + key0); }
;         const bf16* qrow = Qp + (tok0 + q0 + 32 * qsub + r32) * D_ATTN + h * HD + 32 * hi;
;         bf16x8 qf[4];
; #pragma unroll
;         for (int kk = 0; kk < 4; ++kk) qf[kk] = *(const bf16x8*)(qrow + 8 * kk);
; #pragma unroll
;         for (int i = 0; i < 3; ++i) { const int c = tid + 512 * i, row = c >> 3, ch = c & 7, key = q0 - 128 + row;
;             if (key >= 0) *(LAS v4u*)(lds + row * AT_KROW + ch * 16) = kv[i]; }
; #pragma unroll
;         for (int i = 0; i < 3; ++i) { const int c = tid + 512 * i, d = c / 24, ch = c - d * 24, key0 = q0 - 128 + 8 * ch;
;             if (key0 >= 0) { LAS u64* p = (LAS u64*)(lds + AT_V_OFF + d * AT_VROW + ch * 16); p[0] = ((u64)vv[i].y << 32) | vv[i].x; p[1] = ((u64)vv[i].w << 32) | vv[i].z; } }
;         LDS_WAIT(); __syncthreads();
;         f32x16 s[5];
; #pragma unroll
;         for (int kt = 0; kt < 5; ++kt) {
;             if (kt + qsub >= jt0) {
;                 const LAS unsigned char* kp = lds + (32 * (kt + qsub) + r32) * AT_KROW + 64 * hi;
;                 f32x16 acc = {0.f, 0.f, 0.f, 0.f, 0.f, 0.f, 0.f, 0.f, 0.f, 0.f, 0.f, 0.f, 0.f, 0.f, 0.f, 0.f};
; #pragma unroll
.LBB0_654:
	v_writelane_b32 v254, s88, 53
	v_mov_b32_e32 v4, v0
	s_mov_b32 s15, 0x2aaaaaab
	v_writelane_b32 v254, s89, 54
	v_writelane_b32 v254, s2, 55
	v_readfirstlane_b32 s68, v4
	s_lshr_b32 s0, s68, 6
	v_writelane_b32 v254, s3, 56
	v_writelane_b32 v254, s0, 57
	s_lshl_b32 s0, s90, 6
	v_mul_hi_i32 v9, v4, s15
	s_bfe_i32 s66, s90, 0x190005
	s_and_b32 s3, s0, 0x7c0
	v_add_u32_e32 v8, 0x200, v4
	v_lshrrev_b32_e32 v13, 31, v9
	v_ashrrev_i32_e32 v9, 2, v9
	s_ashr_i32 s67, s66, 31
	v_mov_b32_e32 v3, s3
	s_sub_i32 s0, 0x80, s3
	v_add_u32_e32 v16, v9, v13
	v_mul_hi_i32 v9, v8, s15
	s_ashr_i32 s2, s68, 8
	s_lshl_b64 s[62:63], s[66:67], 11
	v_sub_co_u32_e32 v3, vcc, 0x7f, v3
	s_lshr_b32 s4, s0, 5
	v_lshrrev_b32_e32 v13, 31, v9
	v_ashrrev_i32_e32 v9, 2, v9
	s_and_b64 s[0:1], vcc, exec
	s_movk_i32 s16, 0xffe8
	v_add_u32_e32 v22, v9, v13
	s_cselect_b32 s28, 0, s4
	v_ashrrev_i32_e32 v25, 3, v8
	v_mad_u64_u32 v[8:9], s[4:5], v22, s16, v[8:9]
	s_add_i32 s14, s3, 0xffffff80
	v_lshlrev_b32_e32 v9, 3, v8
	v_add_u32_e32 v12, 0x400, v4
	v_add_u32_e32 v13, s14, v9
	v_cmp_lt_i32_e64 s[12:13], -1, v13
	v_mul_hi_i32 v13, v12, s15
	v_bfe_u32 v141, v4, 5, 1
	v_lshlrev_b32_e32 v5, 4, v4
	v_lshrrev_b32_e32 v24, 31, v13
	v_ashrrev_i32_e32 v13, 2, v13
	s_lshl_b32 s76, s2, 5
	v_and_b32_e32 v26, 0x70, v5
	v_lshlrev_b32_e32 v5, 2, v141
	v_add_u32_e32 v24, v13, v24
	s_ashr_i32 s77, s76, 31
	v_ashrrev_i32_e32 v30, 3, v12
	v_mad_u64_u32 v[18:19], s[4:5], v16, s16, v[4:5]
	v_mad_u64_u32 v[12:13], s[4:5], v24, s16, v[12:13]
	v_ashrrev_i32_e32 v23, 3, v4
	v_lshlrev_b32_e32 v19, 3, v18
	v_lshlrev_b32_e32 v13, 3, v12
	s_movk_i32 s5, 0x188
	s_cmp_ge_i32 s2, s28
	v_add_u32_e32 v20, s14, v19
	v_cmp_gt_i32_e64 s[16:17], v23, v3
	v_cmp_gt_i32_e64 s[18:19], v25, v3
	v_cmp_gt_i32_e64 s[20:21], v30, v3
	v_cmp_gt_i32_e64 s[22:23], v19, v3
	v_mul_lo_u32 v19, v16, s5
	v_cmp_gt_i32_e64 s[24:25], v9, v3
	v_mul_lo_u32 v9, v22, s5
	v_cmp_gt_i32_e64 s[26:27], v13, v3
	v_mul_lo_u32 v3, v24, s5
	s_cselect_b64 s[82:83], -1, 0
	s_add_i32 s5, s2, 1
	s_cmp_ge_i32 s5, s28
	v_and_b32_e32 v140, 31, v4
	s_cselect_b64 s[72:73], -1, 0
	s_add_i32 s60, s2, 2
	s_movk_i32 s4, 0x90
	v_lshlrev_b32_e32 v34, 4, v8
	v_or_b32_e32 v8, s76, v140
	s_cmp_ge_i32 s60, s28
	v_mul_lo_u32 v36, v8, s4
	v_lshl_or_b32 v8, s5, 5, v140
	s_cselect_b64 s[88:89], -1, 0
	s_add_i32 s69, s2, 3
	v_mul_lo_u32 v37, v8, s4
	v_lshl_or_b32 v8, s60, 5, v140
	s_cmp_ge_i32 s69, s28
	v_mul_lo_u32 v38, v8, s4
	s_cselect_b64 s[96:97], -1, 0
	v_lshl_or_b32 v8, s69, 5, v140
	s_add_i32 s70, s2, 4
	v_mul_lo_u32 v39, v8, s4
	v_lshl_or_b32 v8, s70, 5, v140
	v_mul_lo_u32 v40, v8, s4
	v_or_b32_e32 v8, 2, v5
	v_cmp_gt_u32_e64 s[34:35], v8, v140
	v_or_b32_e32 v8, 3, v5
	v_cmp_gt_u32_e64 s[36:37], v8, v140
	v_or_b32_e32 v8, 8, v5
	v_cmp_gt_u32_e64 s[38:39], v8, v140
	v_or_b32_e32 v8, 9, v5
	v_cmp_gt_u32_e64 s[40:41], v8, v140
	v_or_b32_e32 v8, 10, v5
	v_cmp_gt_u32_e64 s[42:43], v8, v140
	v_or_b32_e32 v8, 11, v5
	v_cmp_gt_u32_e64 s[44:45], v8, v140
	v_or_b32_e32 v8, 16, v5
	v_cmp_gt_u32_e64 s[46:47], v8, v140
	v_or_b32_e32 v8, 17, v5
	v_cmp_gt_u32_e64 s[48:49], v8, v140
	v_or_b32_e32 v8, 18, v5
	v_lshlrev_b32_e32 v28, 6, v141
	v_cmp_gt_u32_e64 s[50:51], v8, v140
	v_or_b32_e32 v8, 19, v5
	v_add_u32_e32 v29, 0, v28
	s_movk_i32 s0, 0xffc8
	v_cmp_gt_u32_e64 s[52:53], v8, v140
	v_or_b32_e32 v8, 24, v5
	v_mad_i32_i24 v17, v141, s0, v29
	v_add_u32_e32 v31, s14, v13
	v_cmp_gt_u32_e64 s[54:55], v8, v140
	v_or_b32_e32 v8, 25, v5
	v_add_u32_e32 v6, s14, v23
	v_add_u32_e32 v10, s14, v25
	v_add_u32_e32 v14, s14, v30
	v_cmp_lt_i32_e64 s[14:15], -1, v31
	v_mul_lo_u32 v31, v23, s4
	v_mul_lo_u32 v32, v25, s4
	s_cmp_ge_i32 s70, s28
	v_cmp_gt_u32_e64 s[56:57], v8, v140
	v_or_b32_e32 v8, 26, v5
	v_lshl_add_u32 v41, s5, 6, v17
	v_lshl_add_u32 v42, s60, 6, v17
	v_lshl_add_u32 v43, s2, 6, v17
	v_lshl_add_u32 v45, s69, 6, v17
	v_lshl_add_u32 v46, s70, 6, v17
	v_ashrrev_i32_e32 v17, 31, v16
	v_ashrrev_i32_e32 v23, 31, v22
	v_ashrrev_i32_e32 v25, 31, v24
	v_mul_lo_u32 v30, v30, s4
	v_add_u32_e32 v33, 0, v9
	v_lshlrev_b32_e32 v35, 4, v12
	s_cselect_b64 s[74:75], -1, 0
	v_cmp_gt_u32_e64 s[58:59], v8, v140
	v_lshlrev_b64 v[8:9], 15, v[16:17]
	s_lshl_b64 s[4:5], s[66:67], 12
	v_lshlrev_b64 v[12:13], 15, v[22:23]
	v_lshlrev_b64 v[16:17], 15, v[24:25]
	v_mov_b32_e32 v21, v2
; __device__ __forceinline__ void attn_phase(LAS unsigned char* lds, int vcu, int G, const bf16* Qp, const bf16* Kp, const bf16* Vt, const float* sinks, bf16* AO, int ldo, float* st) {
;     ...
;     for (int it = 0; it < 4; ++it) { const int id = ((vcu >> 5) << 7) | (it << 5) | (vcu & 31);
;         const int b = id >> 7, kvh = (id >> 5) & 3, q0 = 64 * (id & 31), h = kvh * 4 + hq;
;         const size_t tok0 = (size_t)b * SEQ;
;         const int jt0 = (q0 >= 128) ? 0 : (128 - q0) / 32;
;         v4u kv[3], vv[3];
; #pragma unroll
;         for (int i = 0; i < 3; ++i) { const int c = tid + 512 * i, row = c >> 3, ch = c & 7, key = q0 - 128 + row;
;             if (key >= 0) kv[i] = *(const v4u*)(Kp + (tok0 + key) * D_KV + kvh * HD + ch * 8); }
; #pragma unroll
;         for (int i = 0; i < 3; ++i) { const int c = tid + 512 * i, d = c / 24, ch = c - d * 24, key0 = q0 - 128 + 8 * ch;
;             if (key0 >= 0) vv[i] = *(const v4u*)(Vt + (size_t)(kvh * HD + d) * M + tok0 + key0); }
;         const bf16* qrow = Qp + (tok0 + q0 + 32 * qsub + r32) * D_ATTN + h * HD + 32 * hi;
;         bf16x8 qf[4];
; #pragma unroll
;         for (int kk = 0; kk < 4; ++kk) qf[kk] = *(const bf16x8*)(qrow + 8 * kk);
;     ...
;         const float sk = sinks[h] * 1.4426950408889634f;
	v_cmp_gt_u32_e64 s[28:29], v5, v140
	v_cmp_lt_u32_e64 s[30:31], v5, v140
	v_or_b32_e32 v5, 27, v5
	v_lshl_add_u64 v[8:9], v[8:9], 0, s[4:5]
	v_lshl_add_u64 v[12:13], v[12:13], 0, s[4:5]
	v_lshl_add_u64 v[16:17], v[16:17], 0, s[4:5]
	s_movk_i32 s4, 0xc0
	v_cmp_lt_i32_e64 s[10:11], -1, v20
	v_cmp_gt_u32_e64 s[60:61], v5, v140
	v_lshl_add_u64 v[8:9], v[20:21], 1, v[8:9]
	v_mul_lo_u32 v5, v22, s4
	v_mul_lo_u32 v20, v24, s4
	s_mov_b64 s[4:5], 0xd800000
	v_lshl_add_u64 v[124:125], v[8:9], 0, s[4:5]
	v_lshl_add_u32 v8, v4, 3, s3
	v_sub_u32_e32 v4, v8, v5
	v_add_u32_e32 v4, 0xf80, v4
	v_mov_b32_e32 v5, v2
	v_lshl_add_u64 v[4:5], v[4:5], 1, v[12:13]
	v_lshl_add_u64 v[126:127], v[4:5], 0, s[4:5]
	v_sub_u32_e32 v4, v8, v20
	v_add_u32_e32 v4, 0x1f80, v4
	v_mov_b32_e32 v5, v2
	v_mov_b32_e32 v7, v2
	v_lshl_add_u64 v[4:5], v[4:5], 1, v[16:17]
	v_lshl_add_u64 v[128:129], v[4:5], 0, s[4:5]
	s_lshl_b64 s[4:5], s[66:67], 20
	v_lshlrev_b64 v[4:5], 9, v[6:7]
	v_lshl_add_u64 v[4:5], s[4:5], 0, v[4:5]
	v_mov_b32_e32 v11, v2
	v_or_b32_e32 v4, v4, v26
	s_mov_b64 s[66:67], 0xd000000
	v_lshl_add_u64 v[130:131], v[4:5], 0, s[66:67]
	v_lshlrev_b64 v[4:5], 9, v[10:11]
	v_lshl_add_u64 v[4:5], s[4:5], 0, v[4:5]
	v_mov_b32_e32 v15, v2
	v_or_b32_e32 v4, v4, v26
	v_lshl_add_u64 v[132:133], v[4:5], 0, s[66:67]
	v_lshlrev_b64 v[4:5], 9, v[14:15]
	v_lshl_add_u64 v[4:5], s[4:5], 0, v[4:5]
	s_lshr_b32 s4, s68, 4
	s_and_b32 s4, s4, 12
	s_add_u32 s4, s64, s4
	s_addc_u32 s5, s65, 0
	v_writelane_b32 v254, s90, 58
	v_or_b32_e32 v4, v4, v26
	s_add_u32 s62, s62, s76
	v_lshl_add_u64 v[134:135], v[4:5], 0, s[66:67]
	v_writelane_b32 v254, s76, 59
	s_addc_u32 s63, s63, s77
	v_or_b32_e32 v4, s3, v140
	v_mov_b32_e32 v5, v2
	v_lshl_add_u64 v[4:5], s[62:63], 0, v[4:5]
	s_lshl_b32 s62, s68, 1
	v_cmp_lt_i32_e64 s[0:1], -1, v6
	v_lshlrev_b64 v[6:7], 12, v[4:5]
	s_and_b32 s64, s62, 0x180
	v_lshlrev_b32_e32 v8, 3, v141
	v_or3_b32 v6, v6, s64, v8
	s_mov_b64 s[62:63], 0xf000040
	v_lshlrev_b64 v[4:5], 11, v[4:5]
	v_lshl_add_u64 v[136:137], v[6:7], 0, s[62:63]
	v_or3_b32 v4, v4, s64, v28
	s_mov_b64 s[62:63], 0xb000020
	v_add_u32_e32 v27, 0, v26
	v_add_u32_e32 v19, 0, v19
	v_lshlrev_b32_e32 v18, 4, v18
	v_add_u32_e32 v3, 0, v3
	v_mul_u32_u24_e32 v44, 0x188, v140
	v_writelane_b32 v254, s77, 60
	v_lshl_add_u64 v[138:139], v[4:5], 0, s[62:63]
	s_movk_i32 s62, 0x6c00
	v_cmp_lt_i32_e64 s[6:7], -1, v10
	v_cmp_lt_i32_e64 s[8:9], -1, v14
	v_writelane_b32 v254, s3, 61
	s_mov_b64 s[76:77], 0
	v_add_u32_e32 v142, v27, v31
	v_add_u32_e32 v143, v27, v32
	v_add_u32_e32 v144, v27, v30
	v_add3_u32 v145, v19, v18, s62
	v_add3_u32 v146, v33, v34, s62
	v_add3_u32 v147, v3, v35, s62
	v_add_u32_e32 v148, v29, v36
	v_add_u32_e32 v149, v29, v37
	v_add_u32_e32 v150, v29, v38
	v_add_u32_e32 v151, v29, v39
	v_add_u32_e32 v152, v29, v40
	v_mbcnt_hi_u32_b32 v1, -1, v1
	v_add_u32_e32 v153, v43, v44
	v_add_u32_e32 v154, v41, v44
	v_add_u32_e32 v155, v42, v44
	v_add_u32_e32 v156, v45, v44
	v_add_u32_e32 v157, v46, v44
	s_mov_b64 s[78:79], 0x200000
	s_mov_b64 s[90:91], 0x80
	v_mov_b32_e32 v158, 0xff800000
	v_mov_b32_e32 v159, 0
	s_mov_b32 s3, 0x3fb8aa3b
	s_mov_b64 exec, s[0:1]
	v_lshl_add_u64 v[240:241], s[94:95], 0, v[130:131]
	global_load_dwordx4 v[200:203], v[240:241], off
	s_mov_b64 exec, s[6:7]
	v_lshl_add_u64 v[240:241], s[94:95], 0, v[132:133]
	global_load_dwordx4 v[204:207], v[240:241], off
	s_mov_b64 exec, s[8:9]
	v_lshl_add_u64 v[240:241], s[94:95], 0, v[134:135]
	global_load_dwordx4 v[208:211], v[240:241], off
	s_mov_b64 exec, s[10:11]
	v_lshl_add_u64 v[240:241], s[94:95], 0, v[124:125]
	global_load_dwordx4 v[212:215], v[240:241], off
	s_mov_b64 exec, s[12:13]
	v_lshl_add_u64 v[240:241], s[94:95], 0, v[126:127]
	global_load_dwordx4 v[216:219], v[240:241], off
	s_mov_b64 exec, s[14:15]
	v_lshl_add_u64 v[240:241], s[94:95], 0, v[128:129]
	global_load_dwordx4 v[220:223], v[240:241], off
	s_mov_b64 exec, -1
	v_lshl_add_u64 v[240:241], s[94:95], 0, v[138:139]
	global_load_dwordx4 v[224:227], v[240:241], off offset:-32
	global_load_dwordx4 v[228:231], v[240:241], off offset:-16
	global_load_dwordx4 v[232:235], v[240:241], off
	global_load_dwordx4 v[236:239], v[240:241], off offset:16
	s_add_u32 vcc_lo, s4, s76
	s_addc_u32 vcc_hi, s5, s77
	global_load_dword v242, v2, vcc
	s_waitcnt vmcnt(0)
	s_branch .LBB0_656

; #define LAS __attribute__((address_space(3)))
; __device__ __forceinline__ void attn_phase(LAS unsigned char* lds, int vcu, int G, const bf16* Qp, const bf16* Kp, const bf16* Vt, const float* sinks, bf16* AO, int ldo, float* st) {
;     ...
;         const bf16* qrow = Qp + (tok0 + q0 + 32 * qsub + r32) * D_ATTN + h * HD + 32 * hi;
;         bf16x8 qf[4];
; #pragma unroll
;         for (int kk = 0; kk < 4; ++kk) qf[kk] = *(const bf16x8*)(qrow + 8 * kk);
; #pragma unroll
;         for (int i = 0; i < 3; ++i) { const int c = tid + 512 * i, row = c >> 3, ch = c & 7, key = q0 - 128 + row;
;             if (key >= 0) *(LAS v4u*)(lds + row * AT_KROW + ch * 16) = kv[i]; }
;     ...
;         const float sk = sinks[h] * 1.4426950408889634f;
.LBB0_656:
	s_waitcnt vmcnt(8)
	v_mov_b32_e32 v120, v224
	v_mov_b32_e32 v121, v225
	v_mov_b32_e32 v122, v226
	v_mov_b32_e32 v123, v227
	v_mov_b32_e32 v116, v228
	v_mov_b32_e32 v117, v229
	v_mov_b32_e32 v118, v230
	v_mov_b32_e32 v119, v231
	v_mov_b32_e32 v112, v232
	v_mov_b32_e32 v113, v233
	v_mov_b32_e32 v114, v234
	v_mov_b32_e32 v115, v235
	v_mov_b32_e32 v108, v236
	v_mov_b32_e32 v109, v237
	v_mov_b32_e32 v110, v238
	v_mov_b32_e32 v111, v239
	v_mov_b32_e32 v183, v242
	s_and_saveexec_b64 s[62:63], s[16:17]
	s_cbranch_execnz .LBB0_687
	s_or_b64 exec, exec, s[62:63]
	s_and_saveexec_b64 s[62:63], s[18:19]
	s_cbranch_execnz .LBB0_688

; #define LAS __attribute__((address_space(3)))
; #define LDS_WAIT() asm volatile("s_waitcnt lgkmcnt(0)" ::: "memory")
; __device__ __forceinline__ void attn_phase(LAS unsigned char* lds, int vcu, int G, const bf16* Qp, const bf16* Kp, const bf16* Vt, const float* sinks, bf16* AO, int ldo, float* st) {
;     ...
;         for (int i = 0; i < 3; ++i) { const int c = tid + 512 * i, row = c >> 3, ch = c & 7, key = q0 - 128 + row;
;             if (key >= 0) *(LAS v4u*)(lds + row * AT_KROW + ch * 16) = kv[i]; }
; #pragma unroll
;         for (int i = 0; i < 3; ++i) { const int c = tid + 512 * i, d = c / 24, ch = c - d * 24, key0 = q0 - 128 + 8 * ch;
;             if (key0 >= 0) { LAS u64* p = (LAS u64*)(lds + AT_V_OFF + d * AT_VROW + ch * 16); p[0] = ((u64)vv[i].y << 32) | vv[i].x; p[1] = ((u64)vv[i].w << 32) | vv[i].z; } }
;         LDS_WAIT(); __syncthreads();
;         f32x16 s[5];
; #pragma unroll
;         for (int kt = 0; kt < 5; ++kt) {
;             if (kt + qsub >= jt0) {
;                 const LAS unsigned char* kp = lds + (32 * (kt + qsub) + r32) * AT_KROW + 64 * hi;
;                 f32x16 acc = {0.f, 0.f, 0.f, 0.f, 0.f, 0.f, 0.f, 0.f, 0.f, 0.f, 0.f, 0.f, 0.f, 0.f, 0.f, 0.f};
; #pragma unroll
;                 for (int kk = 0; kk < 4; ++kk) acc = __builtin_amdgcn_mfma_f32_32x32x16_bf16(*(const LAS bf16x8*)(kp + 16 * kk), qf[kk], acc, 0, 0, 0);
;                 s[kt] = acc;
.LBB0_669:
	s_waitcnt vmcnt(8)
	ds_write2_b64 v147, v[220:221], v[222:223] offset1:1
.LBB0_670:
	s_or_b64 exec, exec, s[62:63]
	s_waitcnt lgkmcnt(0)
	v_cndmask_b32_e64 v3, 0, 1, s[82:83]
	v_mov_b32_e32 v4, 0xff800000
	v_cmp_ne_u32_e64 s[64:65], 1, v3
	s_andn2_b64 vcc, exec, s[82:83]
	v_mov_b32_e32 v52, 0xff800000
	v_mov_b32_e32 v53, 0xff800000
	v_mov_b32_e32 v54, 0xff800000
	v_mov_b32_e32 v55, 0xff800000
	v_mov_b32_e32 v56, 0xff800000
	v_mov_b32_e32 v57, 0xff800000
	v_mov_b32_e32 v58, 0xff800000
	v_mov_b32_e32 v59, 0xff800000
	v_mov_b32_e32 v60, 0xff800000
	v_mov_b32_e32 v61, 0xff800000
	v_mov_b32_e32 v62, 0xff800000
	v_mov_b32_e32 v63, 0xff800000
	v_mov_b32_e32 v64, 0xff800000
	v_mov_b32_e32 v65, 0xff800000
	v_mov_b32_e32 v66, 0xff800000
	v_mov_b32_e32 v67, 0xff800000
	s_waitcnt vmcnt(8) lgkmcnt(0)
	s_barrier
	s_cbranch_vccnz .LBB0_672
	ds_read_b128 v[6:9], v148
	s_waitcnt lgkmcnt(0)
	v_mfma_f32_32x32x16_bf16 v[52:67], v[6:9], v[120:123], 0
	ds_read_b128 v[6:9], v148 offset:16
	s_waitcnt lgkmcnt(0)
	v_mfma_f32_32x32x16_bf16 v[52:67], v[6:9], v[116:119], v[52:67]
	ds_read_b128 v[6:9], v148 offset:32
	s_waitcnt lgkmcnt(0)
	v_mfma_f32_32x32x16_bf16 v[52:67], v[6:9], v[112:115], v[52:67]
	ds_read_b128 v[6:9], v148 offset:48
	s_waitcnt lgkmcnt(0)
	v_mfma_f32_32x32x16_bf16 v[52:67], v[6:9], v[108:111], v[52:67]

; #define LAS __attribute__((address_space(3)))
; __device__ __forceinline__ void attn_phase(LAS unsigned char* lds, int vcu, int G, const bf16* Qp, const bf16* Kp, const bf16* Vt, const float* sinks, bf16* AO, int ldo, float* st) {
;     ...
;         for (int i = 0; i < 3; ++i) { const int c = tid + 512 * i, row = c >> 3, ch = c & 7, key = q0 - 128 + row;
;             if (key >= 0) *(LAS v4u*)(lds + row * AT_KROW + ch * 16) = kv[i]; }
; #pragma unroll
;         for (int i = 0; i < 3; ++i) { const int c = tid + 512 * i, d = c / 24, ch = c - d * 24, key0 = q0 - 128 + 8 * ch;
;             if (key0 >= 0) { LAS u64* p = (LAS u64*)(lds + AT_V_OFF + d * AT_VROW + ch * 16); p[0] = ((u64)vv[i].y << 32) | vv[i].x; p[1] = ((u64)vv[i].w << 32) | vv[i].z; } }
.LBB0_687:
	s_waitcnt vmcnt(8)
	ds_write_b128 v142, v[200:203]
	s_or_b64 exec, exec, s[62:63]
	s_and_saveexec_b64 s[62:63], s[18:19]
	s_cbranch_execz .LBB0_665
.LBB0_688:
	s_waitcnt vmcnt(8)
	ds_write_b128 v143, v[204:207]
	s_or_b64 exec, exec, s[62:63]
	s_and_saveexec_b64 s[62:63], s[20:21]
	s_cbranch_execz .LBB0_666
.LBB0_689:
	s_waitcnt vmcnt(8)
	ds_write_b128 v144, v[208:211]
	s_or_b64 exec, exec, s[62:63]
	s_and_saveexec_b64 s[62:63], s[22:23]
	s_cbranch_execz .LBB0_667
.LBB0_690:
	s_waitcnt vmcnt(8)
	ds_write2_b64 v145, v[212:213], v[214:215] offset1:1
	s_or_b64 exec, exec, s[62:63]
	s_and_saveexec_b64 s[62:63], s[24:25]
	s_cbranch_execz .LBB0_668
.LBB0_691:
	s_waitcnt vmcnt(8)
	ds_write2_b64 v146, v[216:217], v[218:219] offset1:1
	s_or_b64 exec, exec, s[62:63]
	s_and_saveexec_b64 s[62:63], s[26:27]
	s_cbranch_execnz .LBB0_669
	s_branch .LBB0_670
